# attention work queues: after own queue is exhausted read all 8 counters once and skip already-exhausted remote queues
# baseline (speedup 1.0000x reference)
; #define GAS __attribute__((address_space(1)))
; __device__ __forceinline__ void attn_phase(const AttnArgs& A, GAS unsigned* counters, LAS unsigned char* lds) {
;     ...
;     const int x0 = (int)(__builtin_amdgcn_s_getreg((3 << 11) | 20) & 7u);
; #pragma unroll 1
;     for (int qn = 0; qn < 8; ++qn) {
;         const int x = (x0 + qn) & 7; GAS unsigned* counter = counters + 64 * x;
;         for (;;) {
;             if (threadIdx.x == 0) *bc = __hip_atomic_fetch_add(counter, 1u, __ATOMIC_RELAXED, __HIP_MEMORY_SCOPE_AGENT);
;             __syncthreads();
;             const int idx = (int)__builtin_amdgcn_readfirstlane(*bc);
;             __syncthreads();
;             if (idx >= 384) break;
.LBB0_346:
	v_readlane_b32 s3, v254, 52
	v_readlane_b32 s1, v254, 49
	v_readlane_b32 s6, v254, 51
	v_readlane_b32 s2, v254, 47
	s_add_i32 s3, s3, 1
	s_addk_i32 s1, 0x100
	s_add_i32 s6, s6, 1
	s_add_i32 s2, s2, 1
	s_cmp_lg_u32 s3, 1
	s_cbranch_scc1 .Lq_nopeek
	v_readlane_b32 s100, v254, 38
	v_readlane_b32 s101, v254, 39
	s_and_saveexec_b64 s[98:99], s[66:67]
	s_cbranch_execz .Lq_pk_skip
	v_mov_b32_e32 v233, 0
	global_load_dword v226, v233, s[100:101] sc1
	global_load_dword v227, v233, s[100:101] offset:256 sc1
	global_load_dword v228, v233, s[100:101] offset:512 sc1
	global_load_dword v229, v233, s[100:101] offset:768 sc1
	global_load_dword v230, v233, s[100:101] offset:1024 sc1
	global_load_dword v231, v233, s[100:101] offset:1280 sc1
	global_load_dword v232, v233, s[100:101] offset:1536 sc1
	global_load_dword v233, v233, s[100:101] offset:1792 sc1
	s_waitcnt vmcnt(0)
	v_cmp_gt_u32_e32 vcc, 0x180, v226
	s_nop 1
	v_cndmask_b32_e64 v226, 0, 1, vcc
	v_cmp_gt_u32_e32 vcc, 0x180, v227
	s_nop 1
	v_cndmask_b32_e64 v227, 0, 1, vcc
	v_lshl_or_b32 v226, v227, 1, v226
	v_cmp_gt_u32_e32 vcc, 0x180, v228
	s_nop 1
	v_cndmask_b32_e64 v228, 0, 1, vcc
	v_lshl_or_b32 v226, v228, 2, v226
	v_cmp_gt_u32_e32 vcc, 0x180, v229
	s_nop 1
	v_cndmask_b32_e64 v229, 0, 1, vcc
	v_lshl_or_b32 v226, v229, 3, v226
	v_cmp_gt_u32_e32 vcc, 0x180, v230
	s_nop 1
	v_cndmask_b32_e64 v230, 0, 1, vcc
	v_lshl_or_b32 v226, v230, 4, v226
	v_cmp_gt_u32_e32 vcc, 0x180, v231
	s_nop 1
	v_cndmask_b32_e64 v231, 0, 1, vcc
	v_lshl_or_b32 v226, v231, 5, v226
	v_cmp_gt_u32_e32 vcc, 0x180, v232
	s_nop 1
	v_cndmask_b32_e64 v232, 0, 1, vcc
	v_lshl_or_b32 v226, v232, 6, v226
	v_cmp_gt_u32_e32 vcc, 0x180, v233
	s_nop 1
	v_cndmask_b32_e64 v233, 0, 1, vcc
	v_lshl_or_b32 v226, v233, 7, v226
	v_mov_b32_e32 v227, s94
	s_nop 0
	ds_write_b32 v227, v226
.Lq_pk_skip:
	s_or_b64 exec, exec, s[98:99]
	s_waitcnt lgkmcnt(0)
	s_barrier
	v_mov_b32_e32 v226, s94
	s_nop 0
	ds_read_b32 v226, v226
	s_waitcnt lgkmcnt(0)
	s_barrier
	v_readfirstlane_b32 s98, v226
	s_nop 3
.Lq_nopeek:
.Lq_skiploop:
	s_cmp_lg_u32 s3, 8
	s_cbranch_scc0 .LBB0_446
	v_readlane_b32 s99, v254, 44
	s_nop 3
	s_add_i32 s99, s99, s3
	s_and_b32 s99, s99, 7
	s_lshr_b32 s99, s98, s99
	s_bitcmp1_b32 s99, 0
	s_cbranch_scc1 .LBB0_347
	s_add_i32 s3, s3, 1
	s_addk_i32 s1, 0x100
	s_add_i32 s6, s6, 1
	s_add_i32 s2, s2, 1
	s_branch .Lq_skiploop

; __global__ void __launch_bounds__(NWAVES * 64, 2) fwd_kernel(Args args) {
	.amdhsa_kernel _Z10fwd_kernel4Args
		.amdhsa_group_segment_fixed_size 0
		.amdhsa_private_segment_fixed_size 0
		.amdhsa_kernarg_size 408
		.amdhsa_user_sgpr_count 2
		.amdhsa_user_sgpr_dispatch_ptr 0
		.amdhsa_user_sgpr_queue_ptr 0
		.amdhsa_user_sgpr_kernarg_segment_ptr 1
		.amdhsa_user_sgpr_dispatch_id 0
		.amdhsa_user_sgpr_kernarg_preload_length 0
		.amdhsa_user_sgpr_kernarg_preload_offset 0
		.amdhsa_user_sgpr_private_segment_size 0
		.amdhsa_uses_dynamic_stack 0
		.amdhsa_enable_private_segment 0
		.amdhsa_system_sgpr_workgroup_id_x 1
		.amdhsa_system_sgpr_workgroup_id_y 0
		.amdhsa_system_sgpr_workgroup_id_z 0
		.amdhsa_system_sgpr_workgroup_info 0
		.amdhsa_system_vgpr_workitem_id 2
		.amdhsa_next_free_vgpr 256
		.amdhsa_next_free_sgpr 102
		.amdhsa_accum_offset 256
		.amdhsa_reserve_vcc 1
		.amdhsa_float_round_mode_32 0
		.amdhsa_float_round_mode_16_64 0
		.amdhsa_float_denorm_mode_32 3
		.amdhsa_float_denorm_mode_16_64 3
		.amdhsa_dx10_clamp 1
		.amdhsa_ieee_mode 1
		.amdhsa_fp16_overflow 0
		.amdhsa_tg_split 0
		.amdhsa_exception_fp_ieee_invalid_op 0
		.amdhsa_exception_fp_denorm_src 0
		.amdhsa_exception_fp_ieee_div_zero 0
		.amdhsa_exception_fp_ieee_overflow 0
		.amdhsa_exception_fp_ieee_underflow 0
		.amdhsa_exception_fp_ieee_inexact 0
		.amdhsa_exception_int_div_zero 0
	.end_amdhsa_kernel

; __global__ void __launch_bounds__(NWAVES * 64, 2) fwd_kernel(Args args) {
amdhsa.kernels:
  - .agpr_count:     0
    .args:
      - .offset:         0
        .size:           152
        .value_kind:     by_value
      - .offset:         152
        .size:           4
        .value_kind:     hidden_block_count_x
      - .offset:         156
        .size:           4
        .value_kind:     hidden_block_count_y
      - .offset:         160
        .size:           4
        .value_kind:     hidden_block_count_z
      - .offset:         164
        .size:           2
        .value_kind:     hidden_group_size_x
      - .offset:         166
        .size:           2
        .value_kind:     hidden_group_size_y
      - .offset:         168
        .size:           2
        .value_kind:     hidden_group_size_z
      - .offset:         170
        .size:           2
        .value_kind:     hidden_remainder_x
      - .offset:         172
        .size:           2
        .value_kind:     hidden_remainder_y
      - .offset:         174
        .size:           2
        .value_kind:     hidden_remainder_z
      - .offset:         192
        .size:           8
        .value_kind:     hidden_global_offset_x
      - .offset:         200
        .size:           8
        .value_kind:     hidden_global_offset_y
      - .offset:         208
        .size:           8
        .value_kind:     hidden_global_offset_z
      - .offset:         216
        .size:           2
        .value_kind:     hidden_grid_dims
      - .offset:         240
        .size:           8
        .value_kind:     hidden_multigrid_sync_arg
      - .offset:         272
        .size:           4
        .value_kind:     hidden_dynamic_lds_size
    .group_segment_fixed_size: 0
    .kernarg_segment_align: 8
    .kernarg_segment_size: 408
    .language:       OpenCL C
    .language_version:
      - 2
      - 0
    .max_flat_workgroup_size: 512
    .name:           _Z10fwd_kernel4Args
    .private_segment_fixed_size: 0
    .sgpr_count:     108
    .sgpr_spill_count: 70
    .symbol:         _Z10fwd_kernel4Args.kd
    .uniform_work_group_size: 1
    .uses_dynamic_stack: false
    .vgpr_count:     256
    .vgpr_spill_count: 0
    .wavefront_size: 64
